# static s_setprio 1 for waves 4-7 at every phase start (non-GEMM phases run with the younger half raised)
# speedup vs baseline: 1.0367x; 1.0015x over previous
; #define LAS __attribute__((address_space(3)))
; #define MFMA32(a, b, c) __builtin_amdgcn_mfma_f32_32x32x16_bf16((a), (b), (c), 0, 0, 0)
; #define TID_LOCAL() int tid_ = threadIdx.x; asm volatile("" : "+v"(tid_)); const int tid = tid_, lane = tid & 63, wid = __builtin_amdgcn_readfirstlane(tid >> 6), gw = bx * 8 + wid; (void)lane; (void)gw; (void)tid
; DI void attn_unit(LAS unsigned char* lds, bf16_t* P, const float* rope, const float* sinks, int unit, int tid, int wid, int lane) {
;     ...
;     const int g = wid >> 1, head = kvh * 4 + g, q = lane & 31, hl = lane >> 5;
;     const float sinkv = sinks[head] * LOG2E;
;     const float cscale = 0.125f * LOG2E;
; #pragma unroll 1
;     for (int sb = 0; sb < 2; ++sb) {
;         const int r0 = 64 * (wid & 1) + 32 * sb;
;         bf16_t* qrow = P + (size_t)(rowblk + r0 + q) * DIN + PC_Q + head * 64;
;         u32x4 qf[4];
; #pragma unroll
;         for (int s = 0; s < 4; ++s) qf[s] = *(const u32x4*)(qrow + 16 * s + 8 * hl);
;         { u32x4 pr; pr.x = __shfl_xor(qf[0].x, 32); pr.y = __shfl_xor(qf[0].y, 32); pr.z = __shfl_xor(qf[0].z, 32); pr.w = __shfl_xor(qf[0].w, 32);
;           rope8(qf[0], pr, rope + (n * 128 + r0 + q) * 16, hl == 1); }
;         f32x16 S[5];
; #pragma unroll
;         for (int kt = 0; kt < 5; ++kt) {
; #pragma unroll
;             for (int i = 0; i < 16; ++i) S[kt][i] = 0.f;
; #pragma unroll
;             for (int s = 0; s < 4; ++s) { const bf16x8 kf = *(const LAS bf16x8*)(Ks + (r0 + 32 * kt + q) * KS_LD + 16 * s + 8 * hl);
;                 S[kt] = MFMA32(kf, __builtin_bit_cast(bf16x8, qf[s]), S[kt]); }
;         }
; #pragma unroll
;         for (int i = 0; i < 16; ++i) { const int kl = 8 * (i >> 2) + 4 * hl + (i & 3);
;             if (kl <= q) S[0][i] = -1e30f;
;             if (kl > q) S[4][i] = -1e30f; }
; __global__ void __launch_bounds__(512, 2) mega_fwd(Params p) {
;     ...
;                 STEP_SYNC();
;                 if (ph == 1) {
;                     TID_LOCAL(); int lx = l; unsigned char* ws = p.ws + (size_t)half * HALF_STRIDE; unsigned char* wg = p.ws; asm volatile("" : "+s"(lx), "+s"(ws), "+s"(wg));
;                     bf16_t* proj = (bf16_t*)(ws + WS_PROJ);
;                     for (int u = bx; u < BPC * 64 * 4; u += G) attn_unit(lds, proj, (const float*)(wg + WS_ROPE), p.in[I_SINKS] + lx * 16, u, tid, wid, lane);
.LBB0_281:
	s_or_b64 exec, exec, s[0:1]
	v_readfirstlane_b32 s16, v162
	s_lshr_b32 s16, s16, 6
	s_cmp_ge_u32 s16, 4
	s_cbranch_scc0 .Lprio_done
	s_setprio 1
.Lprio_done:
	s_cmp_lg_u32 s6, 1
	s_waitcnt lgkmcnt(0)
	s_barrier
	s_cbranch_scc1 .LBB0_329
	v_readlane_b32 s16, v236, 48
	v_readlane_b32 s17, v236, 49
	v_readlane_b32 s16, v236, 58
	v_mov_b32_e32 v114, v162
	v_readlane_b32 s30, v236, 52
	v_readlane_b32 s18, v236, 50
	v_readlane_b32 s19, v236, 51
	v_readlane_b32 s17, v236, 59
	v_readlane_b32 s31, v236, 53
	v_readfirstlane_b32 s12, v114
	v_readlane_b32 s0, v235, 61
	s_mov_b64 s[92:93], s[18:19]
	s_andn2_b64 vcc, exec, s[16:17]
	s_cbranch_vccnz .LBB0_307
	v_and_b32_e32 v3, 7, v114
	v_cmp_lt_i32_e32 vcc, v166, v165
	v_lshlrev_b32_e32 v80, 4, v3
	s_lshl_b32 s0, s0, 4
	v_cndmask_b32_e32 v0, v164, v166, vcc
	v_lshlrev_b32_e32 v115, 2, v0
	v_lshl_add_u64 v[0:1], s[30:31], 0, v[80:81]
	s_mov_b64 s[18:19], 0x10400000
	s_ashr_i32 s1, s0, 31
	v_lshl_add_u64 v[90:91], v[0:1], 0, s[18:19]
	v_add_u32_e32 v1, 0x200, v114
	s_lshl_b64 s[0:1], s[0:1], 2
	v_readlane_b32 s16, v235, 28
	v_ashrrev_i32_e32 v94, 3, v1
	v_add_u32_e32 v1, 0x400, v114
	v_xor_b32_e32 v8, 32, v164
	v_readlane_b32 s17, v235, 29
	s_add_u32 s7, s16, s0
	v_ashrrev_i32_e32 v96, 3, v1
	v_add_u32_e32 v1, 0x600, v114
	v_cmp_lt_i32_e32 vcc, v8, v165
	s_addc_u32 s16, s17, s1
	v_add_u32_e32 v4, 0, v80
	s_movk_i32 s17, 0x1030
	v_ashrrev_i32_e32 v98, 3, v1
	v_bfe_u32 v1, v114, 5, 1
	v_cndmask_b32_e32 v8, v164, v8, vcc
	v_ashrrev_i32_e32 v92, 3, v114
	v_mad_u32_u24 v0, v3, s17, v4
	v_lshlrev_b32_e32 v80, 3, v1
	v_lshlrev_b32_e32 v120, 2, v8
	v_lshlrev_b32_e32 v8, 4, v1
	v_lshlrev_b32_e32 v1, 2, v1
	v_lshl_add_u32 v116, v92, 1, v0
	v_lshl_add_u32 v117, v94, 1, v0
	v_lshl_add_u32 v118, v96, 1, v0
	v_lshl_add_u32 v119, v98, 1, v0
	v_and_b32_e32 v0, 31, v114
	v_or_b32_e32 v9, 2, v1
	v_cmp_gt_u32_e64 s[54:55], v9, v0
	v_or_b32_e32 v9, 3, v1
	v_cmp_gt_u32_e64 s[56:57], v9, v0
	v_or_b32_e32 v9, 8, v1
	v_cmp_gt_u32_e64 s[58:59], v9, v0
	v_or_b32_e32 v9, 9, v1
	v_cmp_gt_u32_e64 s[60:61], v9, v0
	v_or_b32_e32 v9, 10, v1
	v_cmp_gt_u32_e64 s[62:63], v9, v0
	v_or_b32_e32 v9, 11, v1
	v_cmp_gt_u32_e64 s[64:65], v9, v0
	v_or_b32_e32 v9, 16, v1
	v_cmp_gt_u32_e64 s[66:67], v9, v0
	v_or_b32_e32 v9, 17, v1
	v_cmp_gt_u32_e64 s[68:69], v9, v0
	v_or_b32_e32 v9, 18, v1
	v_cmp_gt_u32_e64 s[70:71], v9, v0
	v_or_b32_e32 v9, 19, v1
	v_cmp_gt_u32_e64 s[72:73], v9, v0
	v_or_b32_e32 v9, 24, v1
	s_ashr_i32 s17, s12, 7
	s_and_b32 s25, s12, 64
	v_cmp_gt_u32_e64 s[74:75], v9, v0
	v_or_b32_e32 v9, 25, v1
	s_bfe_u32 s12, s12, 0x10006
	v_and_b32_e32 v2, 63, v114
	v_cmp_gt_u32_e64 s[50:51], v1, v0
	v_cmp_lt_u32_e64 s[52:53], v1, v0
	v_cmp_gt_u32_e64 s[76:77], v9, v0
	v_or_b32_e32 v9, 26, v1
	v_or_b32_e32 v1, 27, v1
	s_lshl_b32 s19, s12, 7
	v_cmp_lt_u32_e64 s[48:49], 31, v2
	v_cmp_gt_u32_e64 s[80:81], v1, v0
	v_or_b32_e32 v1, 32, v2
	v_mov_b32_e32 v2, s19
	s_movk_i32 s19, 0x208
	v_mad_u32_u24 v1, v1, s19, v2
	v_readlane_b32 s21, v235, 21
	s_mulk_i32 s12, 0x2400
	s_movk_i32 s20, 0x90
	v_add3_u32 v121, v1, v80, s21
	v_mad_u32_u24 v1, v0, s19, v2
	v_add3_u32 v122, v1, v80, s21
	v_mov_b32_e32 v1, s12
	v_cmp_gt_u32_e64 s[78:79], v9, v0
	v_or_b32_e32 v100, s25, v0
	v_mad_u32_u24 v0, v0, s20, v1
	v_add3_u32 v123, v0, v8, 0
	v_lshrrev_b32_e32 v0, 1, v114
	v_cmp_gt_u32_e64 s[0:1], 2, v3
	v_cmp_eq_u32_e64 s[36:37], 1, v3
	s_movk_i32 s18, 0x7f
	v_mul_lo_u32 v5, v92, s20
	v_mul_lo_u32 v3, v94, s20
	v_mul_lo_u32 v6, v96, s20
	v_mul_lo_u32 v7, v98, s20
	v_and_b32_e32 v0, 16, v0
	v_mov_b32_e32 v1, v81
	v_cmp_lt_i32_e64 s[40:41], s18, v92
	v_ashrrev_i32_e32 v93, 31, v92
	v_cmp_lt_i32_e64 s[42:43], s18, v94
	v_ashrrev_i32_e32 v95, 31, v94
	v_cmp_lt_i32_e64 s[44:45], s18, v96
	v_ashrrev_i32_e32 v97, 31, v96
	v_cmp_lt_i32_e64 s[46:47], s18, v98
	v_ashrrev_i32_e32 v99, 31, v98
	s_sub_i32 s18, 0x80, s25
	v_lshl_add_u64 v[102:103], s[30:31], 0, v[0:1]
	v_mov_b32_e32 v101, v81
	s_lshl_b32 s19, s17, 6
	v_lshl_add_u64 v[104:105], s[30:31], 0, v[80:81]
	v_add_u32_e32 v124, v4, v5
	v_add_u32_e32 v125, v4, v3
	v_add_u32_e32 v126, v4, v6
	v_add_u32_e32 v127, v4, v7
	v_readlane_b32 s20, v236, 0
	s_mov_b32 s21, s28
	s_branch .LBB0_285
